# P1: nt only on the wide output stores (not the masked dword stores of the key-mean path)
# speedup vs baseline: 1.0078x; 1.0053x over previous
.LBB0_192:
	v_and_b32_e32 v149, 64, v162
	v_xor_b32_e32 v148, 1, v162
	v_add_u32_e32 v149, 64, v149
	v_cmp_lt_i32_e32 vcc, v148, v149
	v_xor_b32_e32 v151, 2, v162
	s_ashr_i32 s5, s4, 31
	v_cndmask_b32_e32 v148, v162, v148, vcc
	v_lshlrev_b32_e32 v150, 2, v148
	v_add_f32_e32 v148, 0, v126
	v_add_f32_e32 v148, v148, v110
	v_add_f32_e32 v148, v148, v94
	v_add_f32_e32 v148, v148, v78
	v_add_f32_e32 v148, v148, v62
	v_add_f32_e32 v148, v148, v46
	v_add_f32_e32 v148, v148, v30
	v_add_f32_e32 v148, v148, v14
	ds_bpermute_b32 v152, v150, v148
	v_cmp_lt_i32_e32 vcc, v151, v149
	s_lshl_b64 s[6:7], s[4:5], 12
	s_add_u32 s5, s80, s6
	v_cndmask_b32_e32 v151, v162, v151, vcc
	v_lshlrev_b32_e32 v151, 2, v151
	s_waitcnt lgkmcnt(0)
	v_add_f32_e32 v148, v148, v152
	ds_bpermute_b32 v153, v151, v148
	v_xor_b32_e32 v152, 4, v162
	v_cmp_lt_i32_e32 vcc, v152, v149
	s_addc_u32 s30, s81, s7
	s_lshl_b64 s[6:7], s[8:9], 2
	v_cndmask_b32_e32 v152, v162, v152, vcc
	v_lshlrev_b32_e32 v152, 2, v152
	s_waitcnt lgkmcnt(0)
	v_add_f32_e32 v148, v148, v153
	ds_bpermute_b32 v154, v152, v148
	v_xor_b32_e32 v153, 8, v162
	v_cmp_lt_i32_e32 vcc, v153, v149
	s_add_u32 s6, s5, s6
	s_addc_u32 s7, s30, s7
	v_cndmask_b32_e32 v149, v162, v153, vcc
	v_lshlrev_b32_e32 v153, 2, v149
	s_waitcnt lgkmcnt(0)
	v_add_f32_e32 v154, v148, v154
	ds_bpermute_b32 v155, v153, v154
	v_lshlrev_b32_e32 v148, 3, v163
	v_ashrrev_i32_e32 v149, 31, v148
	v_lshl_add_u64 v[148:149], v[148:149], 2, s[6:7]
	v_cmp_eq_u32_e32 vcc, 0, v138
	s_and_saveexec_b64 s[62:63], vcc
	s_cbranch_execz .LBB0_194
	s_waitcnt lgkmcnt(0)
	v_add_f32_e32 v154, v154, v155
	global_store_dword v[148:149], v154, off
	s_bitset1_b32 s98, 0
.LBB0_194:
	s_or_b64 exec, exec, s[62:63]
	v_add_f32_e32 v154, 0, v127
	v_add_f32_e32 v154, v154, v111
	v_add_f32_e32 v154, v154, v95
	v_add_f32_e32 v154, v154, v79
	v_add_f32_e32 v154, v154, v63
	v_add_f32_e32 v154, v154, v47
	v_add_f32_e32 v154, v154, v31
	v_add_f32_e32 v154, v154, v15
	s_waitcnt lgkmcnt(0)
	ds_bpermute_b32 v155, v150, v154
	s_waitcnt lgkmcnt(0)
	v_add_f32_e32 v154, v154, v155
	ds_bpermute_b32 v155, v151, v154
	s_waitcnt lgkmcnt(0)
	v_add_f32_e32 v154, v154, v155
	ds_bpermute_b32 v155, v152, v154
	s_waitcnt lgkmcnt(0)
	v_add_f32_e32 v154, v154, v155
	ds_bpermute_b32 v155, v153, v154
	s_and_saveexec_b64 s[62:63], vcc
	s_cbranch_execz .LBB0_196
	s_waitcnt lgkmcnt(0)
	v_add_f32_e32 v154, v154, v155
	global_store_dword v[148:149], v154, off offset:4
	s_bitset1_b32 s98, 1
.LBB0_196:
	s_or_b64 exec, exec, s[62:63]
	v_add_f32_e32 v154, 0, v128
	v_add_f32_e32 v154, v154, v112
	v_add_f32_e32 v154, v154, v96
	v_add_f32_e32 v154, v154, v80
	v_add_f32_e32 v154, v154, v64
	v_add_f32_e32 v154, v154, v48
	v_add_f32_e32 v154, v154, v32
	v_add_f32_e32 v154, v154, v16
	s_waitcnt lgkmcnt(0)
	ds_bpermute_b32 v155, v150, v154
	s_waitcnt lgkmcnt(0)
	v_add_f32_e32 v154, v154, v155
	ds_bpermute_b32 v155, v151, v154
	s_waitcnt lgkmcnt(0)
	v_add_f32_e32 v154, v154, v155
	ds_bpermute_b32 v155, v152, v154
	s_waitcnt lgkmcnt(0)
	v_add_f32_e32 v154, v154, v155
	ds_bpermute_b32 v155, v153, v154
	s_and_saveexec_b64 s[62:63], vcc
	s_cbranch_execz .LBB0_198
	s_waitcnt lgkmcnt(0)
	v_add_f32_e32 v154, v154, v155
	global_store_dword v[148:149], v154, off offset:8
	s_bitset1_b32 s98, 2
.LBB0_198:
	s_or_b64 exec, exec, s[62:63]
	v_add_f32_e32 v154, 0, v129
	v_add_f32_e32 v154, v154, v113
	v_add_f32_e32 v154, v154, v97
	v_add_f32_e32 v154, v154, v81
	v_add_f32_e32 v154, v154, v65
	v_add_f32_e32 v154, v154, v49
	v_add_f32_e32 v154, v154, v33
	v_add_f32_e32 v154, v154, v17
	s_waitcnt lgkmcnt(0)
	ds_bpermute_b32 v155, v150, v154
	s_waitcnt lgkmcnt(0)
	v_add_f32_e32 v154, v154, v155
	ds_bpermute_b32 v155, v151, v154
	s_waitcnt lgkmcnt(0)
	v_add_f32_e32 v154, v154, v155
	ds_bpermute_b32 v155, v152, v154
	s_waitcnt lgkmcnt(0)
	v_add_f32_e32 v154, v154, v155
	ds_bpermute_b32 v155, v153, v154
	s_and_saveexec_b64 s[62:63], vcc
	s_cbranch_execz .LBB0_200
	s_waitcnt lgkmcnt(0)
	v_add_f32_e32 v154, v154, v155
	global_store_dword v[148:149], v154, off offset:12
	s_bitset1_b32 s98, 3
.LBB0_200:
	s_or_b64 exec, exec, s[62:63]
	v_add_f32_e32 v154, 0, v122
	v_add_f32_e32 v154, v154, v106
	v_add_f32_e32 v154, v154, v90
	v_add_f32_e32 v154, v154, v74
	v_add_f32_e32 v154, v154, v58
	v_add_f32_e32 v154, v154, v42
	v_add_f32_e32 v154, v154, v26
	v_add_f32_e32 v154, v154, v10
	s_waitcnt lgkmcnt(0)
	ds_bpermute_b32 v155, v150, v154
	s_waitcnt lgkmcnt(0)
	v_add_f32_e32 v154, v154, v155
	ds_bpermute_b32 v155, v151, v154
	s_waitcnt lgkmcnt(0)
	v_add_f32_e32 v154, v154, v155
	ds_bpermute_b32 v155, v152, v154
	s_waitcnt lgkmcnt(0)
	v_add_f32_e32 v154, v154, v155
	ds_bpermute_b32 v155, v153, v154
	s_and_saveexec_b64 s[62:63], vcc
	s_cbranch_execz .LBB0_202
	s_waitcnt lgkmcnt(0)
	v_add_f32_e32 v154, v154, v155
	global_store_dword v[148:149], v154, off offset:16
	s_bitset1_b32 s98, 4
.LBB0_202:
	s_or_b64 exec, exec, s[62:63]
	v_add_f32_e32 v154, 0, v123
	v_add_f32_e32 v154, v154, v107
	v_add_f32_e32 v154, v154, v91
	v_add_f32_e32 v154, v154, v75
	v_add_f32_e32 v154, v154, v59
	v_add_f32_e32 v154, v154, v43
	v_add_f32_e32 v154, v154, v27
	v_add_f32_e32 v154, v154, v11
	s_waitcnt lgkmcnt(0)
	ds_bpermute_b32 v155, v150, v154
	s_waitcnt lgkmcnt(0)
	v_add_f32_e32 v154, v154, v155
	ds_bpermute_b32 v155, v151, v154
	s_waitcnt lgkmcnt(0)
	v_add_f32_e32 v154, v154, v155
	ds_bpermute_b32 v155, v152, v154
	s_waitcnt lgkmcnt(0)
	v_add_f32_e32 v154, v154, v155
	ds_bpermute_b32 v155, v153, v154
	s_and_saveexec_b64 s[62:63], vcc
	s_cbranch_execz .LBB0_204
	s_waitcnt lgkmcnt(0)
	v_add_f32_e32 v154, v154, v155
	global_store_dword v[148:149], v154, off offset:20
	s_bitset1_b32 s98, 5
.LBB0_204:
	s_or_b64 exec, exec, s[62:63]
	v_add_f32_e32 v154, 0, v124
	v_add_f32_e32 v154, v154, v108
	v_add_f32_e32 v154, v154, v92
	v_add_f32_e32 v154, v154, v76
	v_add_f32_e32 v154, v154, v60
	v_add_f32_e32 v154, v154, v44
	v_add_f32_e32 v154, v154, v28
	v_add_f32_e32 v154, v154, v12
	s_waitcnt lgkmcnt(0)
	ds_bpermute_b32 v155, v150, v154
	s_waitcnt lgkmcnt(0)
	v_add_f32_e32 v154, v154, v155
	ds_bpermute_b32 v155, v151, v154
	s_waitcnt lgkmcnt(0)
	v_add_f32_e32 v154, v154, v155
	ds_bpermute_b32 v155, v152, v154
	s_waitcnt lgkmcnt(0)
	v_add_f32_e32 v154, v154, v155
	ds_bpermute_b32 v155, v153, v154
	s_and_saveexec_b64 s[62:63], vcc
	s_cbranch_execz .LBB0_206
	s_waitcnt lgkmcnt(0)
	v_add_f32_e32 v154, v154, v155
	global_store_dword v[148:149], v154, off offset:24
	s_bitset1_b32 s98, 6
.LBB0_206:
	s_or_b64 exec, exec, s[62:63]
	v_add_f32_e32 v154, 0, v125
	v_add_f32_e32 v154, v154, v109
	v_add_f32_e32 v154, v154, v93
	v_add_f32_e32 v154, v154, v77
	v_add_f32_e32 v154, v154, v61
	v_add_f32_e32 v154, v154, v45
	v_add_f32_e32 v154, v154, v29
	v_add_f32_e32 v154, v154, v13
	s_waitcnt lgkmcnt(0)
	ds_bpermute_b32 v155, v150, v154
	s_waitcnt lgkmcnt(0)
	v_add_f32_e32 v154, v154, v155
	ds_bpermute_b32 v155, v151, v154
	s_waitcnt lgkmcnt(0)
	v_add_f32_e32 v154, v154, v155
	ds_bpermute_b32 v155, v152, v154
	s_waitcnt lgkmcnt(0)
	v_add_f32_e32 v154, v154, v155
	ds_bpermute_b32 v155, v153, v154
	s_and_saveexec_b64 s[62:63], vcc
	s_cbranch_execz .LBB0_208
	s_waitcnt lgkmcnt(0)
	v_add_f32_e32 v154, v154, v155
	global_store_dword v[148:149], v154, off offset:28
	s_bitset1_b32 s98, 7
.LBB0_208:
	s_or_b64 exec, exec, s[62:63]
	v_add_f32_e32 v154, 0, v118
	v_add_f32_e32 v154, v154, v102
	v_add_f32_e32 v154, v154, v86
	v_add_f32_e32 v154, v154, v70
	v_add_f32_e32 v154, v154, v54
	v_add_f32_e32 v154, v154, v38
	v_add_f32_e32 v154, v154, v22
	v_add_f32_e32 v154, v154, v6
	s_waitcnt lgkmcnt(0)
	ds_bpermute_b32 v155, v150, v154
	s_waitcnt lgkmcnt(0)
	v_add_f32_e32 v154, v154, v155
	ds_bpermute_b32 v155, v151, v154
	s_waitcnt lgkmcnt(0)
	v_add_f32_e32 v154, v154, v155
	ds_bpermute_b32 v155, v152, v154
	s_waitcnt lgkmcnt(0)
	v_add_f32_e32 v154, v154, v155
	ds_bpermute_b32 v155, v153, v154
	s_and_saveexec_b64 s[62:63], vcc
	s_cbranch_execz .LBB0_210
	s_waitcnt lgkmcnt(0)
	v_add_f32_e32 v154, v154, v155
	global_store_dword v[148:149], v154, off offset:128
	s_bitset1_b32 s98, 8
.LBB0_210:
	s_or_b64 exec, exec, s[62:63]
	v_add_f32_e32 v154, 0, v119
	v_add_f32_e32 v154, v154, v103
	v_add_f32_e32 v154, v154, v87
	v_add_f32_e32 v154, v154, v71
	v_add_f32_e32 v154, v154, v55
	v_add_f32_e32 v154, v154, v39
	v_add_f32_e32 v154, v154, v23
	v_add_f32_e32 v154, v154, v7
	s_waitcnt lgkmcnt(0)
	ds_bpermute_b32 v155, v150, v154
	s_waitcnt lgkmcnt(0)
	v_add_f32_e32 v154, v154, v155
	ds_bpermute_b32 v155, v151, v154
	s_waitcnt lgkmcnt(0)
	v_add_f32_e32 v154, v154, v155
	ds_bpermute_b32 v155, v152, v154
	s_waitcnt lgkmcnt(0)
	v_add_f32_e32 v154, v154, v155
	ds_bpermute_b32 v155, v153, v154
	s_and_saveexec_b64 s[62:63], vcc
	s_cbranch_execz .LBB0_212
	s_waitcnt lgkmcnt(0)
	v_add_f32_e32 v154, v154, v155
	global_store_dword v[148:149], v154, off offset:132
	s_bitset1_b32 s98, 9
.LBB0_212:
	s_or_b64 exec, exec, s[62:63]
	v_add_f32_e32 v154, 0, v120
	v_add_f32_e32 v154, v154, v104
	v_add_f32_e32 v154, v154, v88
	v_add_f32_e32 v154, v154, v72
	v_add_f32_e32 v154, v154, v56
	v_add_f32_e32 v154, v154, v40
	v_add_f32_e32 v154, v154, v24
	v_add_f32_e32 v154, v154, v8
	s_waitcnt lgkmcnt(0)
	ds_bpermute_b32 v155, v150, v154
	s_waitcnt lgkmcnt(0)
	v_add_f32_e32 v154, v154, v155
	ds_bpermute_b32 v155, v151, v154
	s_waitcnt lgkmcnt(0)
	v_add_f32_e32 v154, v154, v155
	ds_bpermute_b32 v155, v152, v154
	s_waitcnt lgkmcnt(0)
	v_add_f32_e32 v154, v154, v155
	ds_bpermute_b32 v155, v153, v154
	s_and_saveexec_b64 s[62:63], vcc
	s_cbranch_execz .LBB0_214
	s_waitcnt lgkmcnt(0)
	v_add_f32_e32 v154, v154, v155
	global_store_dword v[148:149], v154, off offset:136
	s_bitset1_b32 s98, 10
.LBB0_214:
	s_or_b64 exec, exec, s[62:63]
	v_add_f32_e32 v154, 0, v121
	v_add_f32_e32 v154, v154, v105
	v_add_f32_e32 v154, v154, v89
	v_add_f32_e32 v154, v154, v73
	v_add_f32_e32 v154, v154, v57
	v_add_f32_e32 v154, v154, v41
	v_add_f32_e32 v154, v154, v25
	v_add_f32_e32 v154, v154, v9
	s_waitcnt lgkmcnt(0)
	ds_bpermute_b32 v155, v150, v154
	s_waitcnt lgkmcnt(0)
	v_add_f32_e32 v154, v154, v155
	ds_bpermute_b32 v155, v151, v154
	s_waitcnt lgkmcnt(0)
	v_add_f32_e32 v154, v154, v155
	ds_bpermute_b32 v155, v152, v154
	s_waitcnt lgkmcnt(0)
	v_add_f32_e32 v154, v154, v155
	ds_bpermute_b32 v155, v153, v154
	s_and_saveexec_b64 s[62:63], vcc
	s_cbranch_execz .LBB0_216
	s_waitcnt lgkmcnt(0)
	v_add_f32_e32 v154, v154, v155
	global_store_dword v[148:149], v154, off offset:140
	s_bitset1_b32 s98, 11
.LBB0_216:
	s_or_b64 exec, exec, s[62:63]
	v_add_f32_e32 v154, 0, v114
	v_add_f32_e32 v154, v154, v98
	v_add_f32_e32 v154, v154, v82
	v_add_f32_e32 v154, v154, v66
	v_add_f32_e32 v154, v154, v50
	v_add_f32_e32 v154, v154, v34
	v_add_f32_e32 v154, v154, v18
	v_add_f32_e32 v154, v154, v2
	s_waitcnt lgkmcnt(0)
	ds_bpermute_b32 v155, v150, v154
	s_waitcnt lgkmcnt(0)
	v_add_f32_e32 v154, v154, v155
	ds_bpermute_b32 v155, v151, v154
	s_waitcnt lgkmcnt(0)
	v_add_f32_e32 v154, v154, v155
	ds_bpermute_b32 v155, v152, v154
	s_waitcnt lgkmcnt(0)
	v_add_f32_e32 v154, v154, v155
	ds_bpermute_b32 v155, v153, v154
	s_and_saveexec_b64 s[62:63], vcc
	s_cbranch_execz .LBB0_218
	s_waitcnt lgkmcnt(0)
	v_add_f32_e32 v154, v154, v155
	global_store_dword v[148:149], v154, off offset:144
	s_bitset1_b32 s98, 12
.LBB0_218:
	s_or_b64 exec, exec, s[62:63]
	v_add_f32_e32 v154, 0, v115
	v_add_f32_e32 v154, v154, v99
	v_add_f32_e32 v154, v154, v83
	v_add_f32_e32 v154, v154, v67
	v_add_f32_e32 v154, v154, v51
	v_add_f32_e32 v154, v154, v35
	v_add_f32_e32 v154, v154, v19
	v_add_f32_e32 v154, v154, v3
	s_waitcnt lgkmcnt(0)
	ds_bpermute_b32 v155, v150, v154
	s_waitcnt lgkmcnt(0)
	v_add_f32_e32 v154, v154, v155
	ds_bpermute_b32 v155, v151, v154
	s_waitcnt lgkmcnt(0)
	v_add_f32_e32 v154, v154, v155
	ds_bpermute_b32 v155, v152, v154
	s_waitcnt lgkmcnt(0)
	v_add_f32_e32 v154, v154, v155
	ds_bpermute_b32 v155, v153, v154
	s_and_saveexec_b64 s[62:63], vcc
	s_cbranch_execz .LBB0_220
	s_waitcnt lgkmcnt(0)
	v_add_f32_e32 v154, v154, v155
	global_store_dword v[148:149], v154, off offset:148
	s_bitset1_b32 s98, 13
.LBB0_220:
	s_or_b64 exec, exec, s[62:63]
	v_add_f32_e32 v154, 0, v116
	v_add_f32_e32 v154, v154, v100
	v_add_f32_e32 v154, v154, v84
	v_add_f32_e32 v154, v154, v68
	v_add_f32_e32 v154, v154, v52
	v_add_f32_e32 v154, v154, v36
	v_add_f32_e32 v154, v154, v20
	v_add_f32_e32 v154, v154, v4
	s_waitcnt lgkmcnt(0)
	ds_bpermute_b32 v155, v150, v154
	s_waitcnt lgkmcnt(0)
	v_add_f32_e32 v154, v154, v155
	ds_bpermute_b32 v155, v151, v154
	s_waitcnt lgkmcnt(0)
	v_add_f32_e32 v154, v154, v155
	ds_bpermute_b32 v155, v152, v154
	s_waitcnt lgkmcnt(0)
	v_add_f32_e32 v154, v154, v155
	ds_bpermute_b32 v155, v153, v154
	s_and_saveexec_b64 s[62:63], vcc
	s_cbranch_execz .LBB0_222
	s_waitcnt lgkmcnt(0)
	v_add_f32_e32 v154, v154, v155
	global_store_dword v[148:149], v154, off offset:152
	s_bitset1_b32 s98, 14
.LBB0_222:
	s_or_b64 exec, exec, s[62:63]
	v_add_f32_e32 v154, 0, v117
	v_add_f32_e32 v154, v154, v101
	v_add_f32_e32 v154, v154, v85
	v_add_f32_e32 v154, v154, v69
	v_add_f32_e32 v154, v154, v53
	v_add_f32_e32 v154, v154, v37
	v_add_f32_e32 v154, v154, v21
	v_add_f32_e32 v154, v154, v5
	ds_bpermute_b32 v150, v150, v154
	s_waitcnt lgkmcnt(0)
	v_add_f32_e32 v150, v154, v150
	ds_bpermute_b32 v151, v151, v150
	s_waitcnt lgkmcnt(0)
	v_add_f32_e32 v150, v150, v151
	ds_bpermute_b32 v151, v152, v150
	s_waitcnt lgkmcnt(0)
	v_add_f32_e32 v150, v150, v151
	ds_bpermute_b32 v151, v153, v150
	s_and_saveexec_b64 s[62:63], vcc
	s_cbranch_execz .LBB0_224
	s_waitcnt lgkmcnt(0)
	v_add_f32_e32 v150, v150, v151
	global_store_dword v[148:149], v150, off offset:156
	s_bitset1_b32 s98, 15
